# s1 item rewritten: coalesced U tile loads at item start, swizzled token-major LDS images via ds_write_b128, MFMA operands via ds_read_b64_tr_b16, batched reads; attention items remapped so neighbourin
# speedup vs baseline: 1.0189x; 1.0104x over previous
.LBB0_316:
	s_cmpk_gt_i32 s24, 0x7f
	s_mov_b64 s[4:5], -1
	s_cbranch_scc0 .LBB0_399
	s_cmpk_gt_u32 s24, 0x9f
	s_cbranch_scc0 .LBB0_323
	v_mov_b32_e32 v18, v201
	v_mov_b32_e32 v0, v201
	v_mov_b32_e32 v2, v201
	s_add_i32 s6, s24, 0xffffff60
	s_barrier
	s_lshl_b32 s2, s6, 6
	v_ashrrev_i32_e32 v2, 6, v2
	s_and_b32 s7, s24, 1
	s_and_b32 s2, s2, 0x7f80
	v_readlane_b32 s100, v253, 46
	v_readlane_b32 s101, v253, 47
	v_lshrrev_b32_e32 v146, 4, v201
	v_or_b32_e32 v146, s2, v146
	v_lshlrev_b32_e32 v146, 11, v146
	v_mov_b32_e32 v147, 0
	v_and_b32_e32 v144, 15, v201
	v_lshlrev_b32_e32 v144, 4, v144
	v_mov_b32_e32 v145, 0
	v_lshl_add_u64 v[146:147], s[100:101], 0, v[146:147]
	v_lshl_add_u64 v[146:147], v[146:147], 0, v[144:145]
	s_lshl_b32 s98, s7, 8
	s_mov_b32 s99, 0
	v_lshl_add_u64 v[144:145], v[146:147], 0, s[98:99]
	s_mov_b32 s98, 0x10000
	global_load_dwordx4 v[96:99], v[144:145], off offset:1024
	v_lshl_add_u64 v[144:145], v[144:145], 0, s[98:99]
	global_load_dwordx4 v[100:103], v[144:145], off offset:1024
	v_lshl_add_u64 v[144:145], v[144:145], 0, s[98:99]
	global_load_dwordx4 v[104:107], v[144:145], off offset:1024
	v_lshl_add_u64 v[144:145], v[144:145], 0, s[98:99]
	global_load_dwordx4 v[108:111], v[144:145], off offset:1024
	v_lshrrev_b32_e32 v146, 5, v201
	v_or_b32_e32 v146, s2, v146
	v_lshlrev_b32_e32 v146, 11, v146
	v_mov_b32_e32 v147, 0
	v_and_b32_e32 v144, 31, v201
	v_lshlrev_b32_e32 v144, 4, v144
	v_mov_b32_e32 v145, 0
	v_lshl_add_u64 v[146:147], s[100:101], 0, v[146:147]
	v_lshl_add_u64 v[146:147], v[146:147], 0, v[144:145]
	s_lshl_b32 s98, s7, 9
	v_lshl_add_u64 v[144:145], v[146:147], 0, s[98:99]
	s_mov_b32 s98, 0x8000
	global_load_dwordx4 v[112:115], v[144:145], off
	v_lshl_add_u64 v[144:145], v[144:145], 0, s[98:99]
	global_load_dwordx4 v[116:119], v[144:145], off
	v_lshl_add_u64 v[144:145], v[144:145], 0, s[98:99]
	global_load_dwordx4 v[120:123], v[144:145], off
	v_lshl_add_u64 v[144:145], v[144:145], 0, s[98:99]
	global_load_dwordx4 v[124:127], v[144:145], off
	v_lshl_add_u64 v[144:145], v[144:145], 0, s[98:99]
	global_load_dwordx4 v[128:131], v[144:145], off
	v_lshl_add_u64 v[144:145], v[144:145], 0, s[98:99]
	global_load_dwordx4 v[132:135], v[144:145], off
	v_lshl_add_u64 v[144:145], v[144:145], 0, s[98:99]
	global_load_dwordx4 v[136:139], v[144:145], off
	v_lshl_add_u64 v[144:145], v[144:145], 0, s[98:99]
	global_load_dwordx4 v[140:143], v[144:145], off
	v_cmp_gt_i32_e32 vcc, 4, v2
	s_and_saveexec_b64 s[4:5], vcc
	s_cbranch_execz .LBB0_320
	v_readlane_b32 s8, v253, 42
	v_readlane_b32 s9, v253, 43
	s_load_dwordx2 s[8:9], s[8:9], 0x90
	v_lshl_add_u32 v4, s7, 2, v2
	v_readlane_b32 s10, v253, 58
	v_and_b32_e32 v3, 63, v0
	v_ashrrev_i32_e32 v5, 31, v4
	v_add_u32_e32 v6, s10, v4
	v_ashrrev_i32_e32 v7, 31, v6
	s_waitcnt lgkmcnt(0)
	v_lshl_add_u64 v[6:7], v[6:7], 2, s[8:9]
	global_load_dword v8, v[6:7], off
	s_lshl_b32 s8, s2, 5
	v_lshl_or_b32 v0, v3, 6, s8
	v_readlane_b32 s8, v254, 11
	v_readlane_b32 s9, v254, 12
	v_add_u32_e32 v10, -4, v243
	v_add_u32_e32 v11, -8, v243
	v_lshl_add_u64 v[6:7], s[8:9], 0, v[0:1]
	v_lshl_add_u64 v[4:5], v[4:5], 2, v[6:7]
	global_load_dword v7, v[4:5], off offset:32
	global_load_dword v6, v[4:5], off
	v_and_b32_e32 v0, 64, v243
	v_add_u32_e32 v4, -1, v243
	v_cmp_lt_i32_e32 vcc, v4, v0
	v_add_u32_e32 v5, -2, v243
	s_waitcnt vmcnt(2)
	v_mul_f32_e32 v8, 0x3fb8aa3b, v8
	v_exp_f32_e32 v8, v8
	v_cndmask_b32_e32 v4, v4, v243, vcc
	v_lshlrev_b32_e32 v4, 2, v4
	v_cmp_lt_i32_e32 vcc, v5, v0
	s_waitcnt vmcnt(1)
	v_mul_f32_e32 v9, v7, v8
	s_waitcnt vmcnt(0)
	v_fma_f32 v9, v6, -v8, -v9
	ds_bpermute_b32 v4, v4, v9
	v_cndmask_b32_e32 v5, v5, v243, vcc
	v_cmp_eq_u32_e32 vcc, 0, v3
	v_lshlrev_b32_e32 v5, 2, v5
	s_waitcnt lgkmcnt(0)
	v_add_f32_e32 v4, v9, v4
	v_cndmask_b32_e32 v4, v4, v9, vcc
	ds_bpermute_b32 v5, v5, v4
	v_cmp_lt_i32_e32 vcc, v10, v0
	s_waitcnt lgkmcnt(0)
	v_add_f32_e32 v5, v4, v5
	v_cndmask_b32_e32 v10, v10, v243, vcc
	v_cmp_gt_u32_e32 vcc, 2, v3
	v_lshlrev_b32_e32 v10, 2, v10
	s_nop 0
	v_cndmask_b32_e32 v4, v5, v4, vcc
	ds_bpermute_b32 v5, v10, v4
	v_cmp_lt_i32_e32 vcc, v11, v0
	v_add_u32_e32 v10, -16, v243
	s_waitcnt lgkmcnt(0)
	v_add_f32_e32 v5, v4, v5
	v_cndmask_b32_e32 v11, v11, v243, vcc
	v_cmp_gt_u32_e32 vcc, 4, v3
	v_lshlrev_b32_e32 v11, 2, v11
	s_nop 0
	v_cndmask_b32_e32 v4, v5, v4, vcc
	ds_bpermute_b32 v5, v11, v4
	v_cmp_lt_i32_e32 vcc, v10, v0
	v_subrev_u32_e32 v11, 32, v243
	s_waitcnt lgkmcnt(0)
	v_add_f32_e32 v5, v4, v5
	v_cndmask_b32_e32 v10, v10, v243, vcc
	v_cmp_gt_u32_e32 vcc, 8, v3
	v_lshlrev_b32_e32 v10, 2, v10
	s_nop 0
	v_cndmask_b32_e32 v4, v5, v4, vcc
	ds_bpermute_b32 v5, v10, v4
	v_cmp_lt_i32_e32 vcc, v11, v0
	v_lshlrev_b32_e32 v10, 3, v3
	v_lshl_or_b32 v2, v2, 9, v10
	v_cndmask_b32_e32 v0, v11, v243, vcc
	s_waitcnt lgkmcnt(0)
	v_add_f32_e32 v5, v4, v5
	v_cmp_gt_u32_e32 vcc, 16, v3
	v_lshlrev_b32_e32 v0, 2, v0
	v_add_u32_e32 v2, 0, v2
	v_cndmask_b32_e32 v4, v5, v4, vcc
	ds_bpermute_b32 v0, v0, v4
	v_cmp_gt_u32_e32 vcc, 32, v3
	v_add_u32_e32 v5, 0x19800, v2
	v_add_u32_e32 v10, 0x1a000, v2
	s_waitcnt lgkmcnt(0)
	v_add_f32_e32 v0, v4, v0
	v_cndmask_b32_e32 v0, v0, v4, vcc
	v_sub_f32_e32 v0, v0, v9
	v_fma_f32 v2, v6, -v8, v0
	v_fma_f32 v3, v7, -v8, v2
	ds_write_b64 v5, v[2:3]
	ds_write_b64 v10, v[6:7]

.LBB0_322:
	s_or_b64 exec, exec, s[4:5]
	s_waitcnt lgkmcnt(1)
	v_sub_f32_e32 v3, v3, v4
	v_mul_f32_e32 v3, 0x3fb8aa3b, v3
	v_exp_f32_e32 v3, v3
	v_and_b32_e32 v28, 0x7f, v18
	s_waitcnt lgkmcnt(0)
	s_barrier
	v_mul_f32_e32 v2, v2, v3
	ds_write_b32 v0, v2
	v_or_b32_e32 v0, s2, v28
	v_readlane_b32 s8, v253, 46
	v_ashrrev_i32_e32 v2, 4, v18
	v_lshlrev_b32_e32 v0, 11, v0
	v_readlane_b32 s9, v253, 47
	v_and_b32_e32 v6, -8, v2
	s_lshl_b32 s2, s7, 8
	v_lshl_add_u64 v[24:25], s[8:9], 0, v[0:1]
	v_ashrrev_i32_e32 v7, 31, v6
	v_lshl_add_u64 v[20:21], v[24:25], 0, s[2:3]
	v_lshlrev_b64 v[26:27], 1, v[6:7]
	v_lshl_add_u64 v[2:3], v[20:21], 0, v[26:27]
	s_waitcnt lgkmcnt(0)
	s_barrier
	v_bfe_u32 v0, v201, 3, 2
	v_lshrrev_b32_e32 v2, 5, v201
	v_lshl_add_u32 v0, v0, 7, v2
	v_lshlrev_b32_e32 v0, 2, v0
	v_add_u32_e32 v0, 0x1a000, v0
	ds_read_b32 v4, v0
	ds_read_b32 v5, v0 offset:64
	ds_read_b32 v6, v0 offset:128
	ds_read_b32 v7, v0 offset:192
	ds_read_b32 v8, v0 offset:256
	ds_read_b32 v9, v0 offset:320
	ds_read_b32 v10, v0 offset:384
	ds_read_b32 v11, v0 offset:448
	v_lshrrev_b32_e32 v12, 7, v201
	v_lshlrev_b32_e32 v12, 11, v12
	v_bfe_u32 v13, v201, 2, 2
	v_lshl_add_u32 v12, v13, 9, v12
	v_bfe_u32 v13, v201, 4, 3
	v_lshl_add_u32 v12, v13, 6, v12
	v_and_b32_e32 v13, 3, v201
	v_bfe_u32 v14, v201, 6, 2
	v_xor_b32_e32 v13, v13, v14
	v_lshl_add_u32 v12, v13, 4, v12
	v_bfe_u32 v13, v201, 4, 1
	v_lshlrev_b32_e32 v15, 15, v13
	v_lshrrev_b32_e32 v13, 8, v201
	v_lshl_add_u32 v15, v13, 11, v15
	v_bfe_u32 v13, v201, 2, 2
	v_lshl_add_u32 v15, v13, 9, v15
	v_bfe_u32 v13, v201, 5, 3
	v_lshl_add_u32 v15, v13, 6, v15
	v_and_b32_e32 v13, 3, v201
	v_bfe_u32 v14, v201, 7, 2
	v_xor_b32_e32 v13, v13, v14
	v_lshl_add_u32 v15, v13, 4, v15
	v_add_u32_e32 v15, 0x8800, v15
	s_waitcnt vmcnt(11)
	ds_write_b128 v12, v[96:99]
	s_waitcnt vmcnt(10)
	ds_write_b128 v12, v[100:103] offset:8192
	s_waitcnt vmcnt(9)
	ds_write_b128 v12, v[104:107] offset:16384
	s_waitcnt vmcnt(8)
	ds_write_b128 v12, v[108:111] offset:24576
	v_and_b32_e32 v80, 63, v201
	v_lshrrev_b32_e32 v81, 4, v80
	v_and_b32_e32 v82, 15, v80
	v_lshrrev_b32_e32 v83, 2, v82
	v_and_b32_e32 v82, 3, v82
	v_lshlrev_b32_e32 v80, 11, v81
	v_lshl_add_u32 v80, v83, 6, v80
	v_and_b32_e32 v83, 1, v82
	v_lshl_add_u32 v80, v83, 3, v80
	v_and_b32_e32 v81, 1, v81
	v_lshrrev_b32_e32 v82, 1, v82
	v_xor_b32_e32 v83, 1, v81
	v_xor_b32_e32 v92, 1, v82
	v_lshl_add_u32 v93, v81, 5, v80
	v_lshl_add_u32 v94, v83, 5, v80
	v_lshl_add_u32 v84, v82, 4, v93
	v_lshl_add_u32 v85, v92, 4, v93
	v_add_u32_e32 v85, 0x100, v85
	v_lshl_add_u32 v86, v82, 4, v94
	v_lshl_add_u32 v87, v92, 4, v94
	v_add_u32_e32 v87, 0x100, v87
	v_lshrrev_b32_e32 v80, 6, v201
	v_lshrrev_b32_e32 v81, 2, v80
	v_and_b32_e32 v80, 3, v80
	v_lshlrev_b32_e32 v81, 15, v81
	v_lshl_add_u32 v81, v80, 9, v81
	v_add_u32_e32 v81, 0x8800, v81
	v_add_u32_e32 v88, v84, v81
	v_add_u32_e32 v89, v85, v81
	v_add_u32_e32 v90, v86, v81
	v_add_u32_e32 v91, v87, v81
	s_waitcnt lgkmcnt(0)
	s_waitcnt vmcnt(7)
	v_lshlrev_b32_e32 v16, 16, v112
	v_and_b32_e32 v17, 0xffff0000, v112
	v_mul_f32_e32 v16, v4, v16
	v_mul_f32_e32 v17, v4, v17
	v_cvt_pk_bf16_f32 v20, v16, v17
	v_lshlrev_b32_e32 v16, 16, v113
	v_and_b32_e32 v17, 0xffff0000, v113
	v_mul_f32_e32 v16, v4, v16
	v_mul_f32_e32 v17, v4, v17
	v_cvt_pk_bf16_f32 v21, v16, v17
	v_lshlrev_b32_e32 v16, 16, v114
	v_and_b32_e32 v17, 0xffff0000, v114
	v_mul_f32_e32 v16, v4, v16
	v_mul_f32_e32 v17, v4, v17
	v_cvt_pk_bf16_f32 v22, v16, v17
	v_lshlrev_b32_e32 v16, 16, v115
	v_and_b32_e32 v17, 0xffff0000, v115
	v_mul_f32_e32 v16, v4, v16
	v_mul_f32_e32 v17, v4, v17
	v_cvt_pk_bf16_f32 v23, v16, v17
	ds_write_b128 v15, v[20:23]
	s_waitcnt vmcnt(6)
	v_lshlrev_b32_e32 v16, 16, v116
	v_and_b32_e32 v17, 0xffff0000, v116
	v_mul_f32_e32 v16, v5, v16
	v_mul_f32_e32 v17, v5, v17
	v_cvt_pk_bf16_f32 v24, v16, v17
	v_lshlrev_b32_e32 v16, 16, v117
	v_and_b32_e32 v17, 0xffff0000, v117
	v_mul_f32_e32 v16, v5, v16
	v_mul_f32_e32 v17, v5, v17
	v_cvt_pk_bf16_f32 v25, v16, v17
	v_lshlrev_b32_e32 v16, 16, v118
	v_and_b32_e32 v17, 0xffff0000, v118
	v_mul_f32_e32 v16, v5, v16
	v_mul_f32_e32 v17, v5, v17
	v_cvt_pk_bf16_f32 v26, v16, v17
	v_lshlrev_b32_e32 v16, 16, v119
	v_and_b32_e32 v17, 0xffff0000, v119
	v_mul_f32_e32 v16, v5, v16
	v_mul_f32_e32 v17, v5, v17
	v_cvt_pk_bf16_f32 v27, v16, v17
	ds_write_b128 v15, v[24:27] offset:4096
	s_waitcnt vmcnt(5)
	v_lshlrev_b32_e32 v16, 16, v120
	v_and_b32_e32 v17, 0xffff0000, v120
	v_mul_f32_e32 v16, v6, v16
	v_mul_f32_e32 v17, v6, v17
	v_cvt_pk_bf16_f32 v20, v16, v17
	v_lshlrev_b32_e32 v16, 16, v121
	v_and_b32_e32 v17, 0xffff0000, v121
	v_mul_f32_e32 v16, v6, v16
	v_mul_f32_e32 v17, v6, v17
	v_cvt_pk_bf16_f32 v21, v16, v17
	v_lshlrev_b32_e32 v16, 16, v122
	v_and_b32_e32 v17, 0xffff0000, v122
	v_mul_f32_e32 v16, v6, v16
	v_mul_f32_e32 v17, v6, v17
	v_cvt_pk_bf16_f32 v22, v16, v17
	v_lshlrev_b32_e32 v16, 16, v123
	v_and_b32_e32 v17, 0xffff0000, v123
	v_mul_f32_e32 v16, v6, v16
	v_mul_f32_e32 v17, v6, v17
	v_cvt_pk_bf16_f32 v23, v16, v17
	ds_write_b128 v15, v[20:23] offset:8192
	s_waitcnt vmcnt(4)
	v_lshlrev_b32_e32 v16, 16, v124
	v_and_b32_e32 v17, 0xffff0000, v124
	v_mul_f32_e32 v16, v7, v16
	v_mul_f32_e32 v17, v7, v17
	v_cvt_pk_bf16_f32 v24, v16, v17
	v_lshlrev_b32_e32 v16, 16, v125
	v_and_b32_e32 v17, 0xffff0000, v125
	v_mul_f32_e32 v16, v7, v16
	v_mul_f32_e32 v17, v7, v17
	v_cvt_pk_bf16_f32 v25, v16, v17
	v_lshlrev_b32_e32 v16, 16, v126
	v_and_b32_e32 v17, 0xffff0000, v126
	v_mul_f32_e32 v16, v7, v16
	v_mul_f32_e32 v17, v7, v17
	v_cvt_pk_bf16_f32 v26, v16, v17
	v_lshlrev_b32_e32 v16, 16, v127
	v_and_b32_e32 v17, 0xffff0000, v127
	v_mul_f32_e32 v16, v7, v16
	v_mul_f32_e32 v17, v7, v17
	v_cvt_pk_bf16_f32 v27, v16, v17
	ds_write_b128 v15, v[24:27] offset:12288
	s_waitcnt vmcnt(3)
	v_lshlrev_b32_e32 v16, 16, v128
	v_and_b32_e32 v17, 0xffff0000, v128
	v_mul_f32_e32 v16, v8, v16
	v_mul_f32_e32 v17, v8, v17
	v_cvt_pk_bf16_f32 v20, v16, v17
	v_lshlrev_b32_e32 v16, 16, v129
	v_and_b32_e32 v17, 0xffff0000, v129
	v_mul_f32_e32 v16, v8, v16
	v_mul_f32_e32 v17, v8, v17
	v_cvt_pk_bf16_f32 v21, v16, v17
	v_lshlrev_b32_e32 v16, 16, v130
	v_and_b32_e32 v17, 0xffff0000, v130
	v_mul_f32_e32 v16, v8, v16
	v_mul_f32_e32 v17, v8, v17
	v_cvt_pk_bf16_f32 v22, v16, v17
	v_lshlrev_b32_e32 v16, 16, v131
	v_and_b32_e32 v17, 0xffff0000, v131
	v_mul_f32_e32 v16, v8, v16
	v_mul_f32_e32 v17, v8, v17
	v_cvt_pk_bf16_f32 v23, v16, v17
	ds_write_b128 v15, v[20:23] offset:16384
	s_waitcnt vmcnt(2)
	v_lshlrev_b32_e32 v16, 16, v132
	v_and_b32_e32 v17, 0xffff0000, v132
	v_mul_f32_e32 v16, v9, v16
	v_mul_f32_e32 v17, v9, v17
	v_cvt_pk_bf16_f32 v24, v16, v17
	v_lshlrev_b32_e32 v16, 16, v133
	v_and_b32_e32 v17, 0xffff0000, v133
	v_mul_f32_e32 v16, v9, v16
	v_mul_f32_e32 v17, v9, v17
	v_cvt_pk_bf16_f32 v25, v16, v17
	v_lshlrev_b32_e32 v16, 16, v134
	v_and_b32_e32 v17, 0xffff0000, v134
	v_mul_f32_e32 v16, v9, v16
	v_mul_f32_e32 v17, v9, v17
	v_cvt_pk_bf16_f32 v26, v16, v17
	v_lshlrev_b32_e32 v16, 16, v135
	v_and_b32_e32 v17, 0xffff0000, v135
	v_mul_f32_e32 v16, v9, v16
	v_mul_f32_e32 v17, v9, v17
	v_cvt_pk_bf16_f32 v27, v16, v17
	ds_write_b128 v15, v[24:27] offset:20480
	s_waitcnt vmcnt(1)
	v_lshlrev_b32_e32 v16, 16, v136
	v_and_b32_e32 v17, 0xffff0000, v136
	v_mul_f32_e32 v16, v10, v16
	v_mul_f32_e32 v17, v10, v17
	v_cvt_pk_bf16_f32 v20, v16, v17
	v_lshlrev_b32_e32 v16, 16, v137
	v_and_b32_e32 v17, 0xffff0000, v137
	v_mul_f32_e32 v16, v10, v16
	v_mul_f32_e32 v17, v10, v17
	v_cvt_pk_bf16_f32 v21, v16, v17
	v_lshlrev_b32_e32 v16, 16, v138
	v_and_b32_e32 v17, 0xffff0000, v138
	v_mul_f32_e32 v16, v10, v16
	v_mul_f32_e32 v17, v10, v17
	v_cvt_pk_bf16_f32 v22, v16, v17
	v_lshlrev_b32_e32 v16, 16, v139
	v_and_b32_e32 v17, 0xffff0000, v139
	v_mul_f32_e32 v16, v10, v16
	v_mul_f32_e32 v17, v10, v17
	v_cvt_pk_bf16_f32 v23, v16, v17
	ds_write_b128 v15, v[20:23] offset:24576
	s_waitcnt vmcnt(0)
	v_lshlrev_b32_e32 v16, 16, v140
	v_and_b32_e32 v17, 0xffff0000, v140
	v_mul_f32_e32 v16, v11, v16
	v_mul_f32_e32 v17, v11, v17
	v_cvt_pk_bf16_f32 v24, v16, v17
	v_lshlrev_b32_e32 v16, 16, v141
	v_and_b32_e32 v17, 0xffff0000, v141
	v_mul_f32_e32 v16, v11, v16
	v_mul_f32_e32 v17, v11, v17
	v_cvt_pk_bf16_f32 v25, v16, v17
	v_lshlrev_b32_e32 v16, 16, v142
	v_and_b32_e32 v17, 0xffff0000, v142
	v_mul_f32_e32 v16, v11, v16
	v_mul_f32_e32 v17, v11, v17
	v_cvt_pk_bf16_f32 v26, v16, v17
	v_lshlrev_b32_e32 v16, 16, v143
	v_and_b32_e32 v17, 0xffff0000, v143
	v_mul_f32_e32 v16, v11, v16
	v_mul_f32_e32 v17, v11, v17
	v_cvt_pk_bf16_f32 v27, v16, v17
	ds_write_b128 v15, v[24:27] offset:28672
	s_waitcnt lgkmcnt(0)
	s_barrier
	ds_read_b64_tr_b16 v[96:97], v88
	ds_read_b64_tr_b16 v[98:99], v89
	ds_read_b64_tr_b16 v[100:101], v90
	ds_read_b64_tr_b16 v[102:103], v91
	ds_read_b64_tr_b16 v[104:105], v84
	ds_read_b64_tr_b16 v[106:107], v85
	ds_read_b64_tr_b16 v[108:109], v86
	ds_read_b64_tr_b16 v[110:111], v87
	ds_read_b64_tr_b16 v[112:113], v84 offset:512
	ds_read_b64_tr_b16 v[114:115], v85 offset:512
	s_waitcnt lgkmcnt(5)
	ds_read_b64_tr_b16 v[116:117], v86 offset:512
	ds_read_b64_tr_b16 v[118:119], v87 offset:512
	ds_read_b64_tr_b16 v[120:121], v84 offset:1024
	ds_read_b64_tr_b16 v[122:123], v85 offset:1024
	ds_read_b64_tr_b16 v[124:125], v86 offset:1024
	ds_read_b64_tr_b16 v[126:127], v87 offset:1024
	ds_read_b64_tr_b16 v[128:129], v84 offset:1536
	ds_read_b64_tr_b16 v[130:131], v85 offset:1536
	ds_read_b64_tr_b16 v[132:133], v86 offset:1536
	ds_read_b64_tr_b16 v[134:135], v87 offset:1536
	s_waitcnt lgkmcnt(0)
	ds_read_b64_tr_b16 v[136:137], v88 offset:8192
	ds_read_b64_tr_b16 v[138:139], v89 offset:8192
	ds_read_b64_tr_b16 v[140:141], v90 offset:8192
	ds_read_b64_tr_b16 v[142:143], v91 offset:8192
	ds_read_b64_tr_b16 v[144:145], v84 offset:8192
	ds_read_b64_tr_b16 v[146:147], v85 offset:8192
	ds_read_b64_tr_b16 v[148:149], v86 offset:8192
	ds_read_b64_tr_b16 v[150:151], v87 offset:8192
	ds_read_b64_tr_b16 v[152:153], v84 offset:8704
	ds_read_b64_tr_b16 v[154:155], v85 offset:8704
	v_mfma_f32_16x16x32_bf16 v[16:19], v[104:107], v[96:99], 0
	v_mfma_f32_16x16x32_bf16 v[20:23], v[108:111], v[96:99], 0
	v_mfma_f32_16x16x32_bf16 v[24:27], v[112:115], v[96:99], 0
	v_mfma_f32_16x16x32_bf16 v[28:31], v[116:119], v[96:99], 0
	v_mfma_f32_16x16x32_bf16 v[32:35], v[120:123], v[96:99], 0
	v_mfma_f32_16x16x32_bf16 v[36:39], v[124:127], v[96:99], 0
	v_mfma_f32_16x16x32_bf16 v[40:43], v[128:131], v[96:99], 0
	v_mfma_f32_16x16x32_bf16 v[44:47], v[132:135], v[96:99], 0
	s_waitcnt lgkmcnt(5)
	ds_read_b64_tr_b16 v[156:157], v86 offset:8704
	ds_read_b64_tr_b16 v[158:159], v87 offset:8704
	ds_read_b64_tr_b16 v[160:161], v84 offset:9216
	ds_read_b64_tr_b16 v[162:163], v85 offset:9216
	ds_read_b64_tr_b16 v[164:165], v86 offset:9216
	ds_read_b64_tr_b16 v[166:167], v87 offset:9216
	ds_read_b64_tr_b16 v[168:169], v84 offset:9728
	ds_read_b64_tr_b16 v[170:171], v85 offset:9728
	ds_read_b64_tr_b16 v[172:173], v86 offset:9728
	ds_read_b64_tr_b16 v[174:175], v87 offset:9728
	v_mfma_f32_16x16x32_bf16 v[48:51], v[104:107], v[100:103], 0
	v_mfma_f32_16x16x32_bf16 v[52:55], v[108:111], v[100:103], 0
	v_mfma_f32_16x16x32_bf16 v[56:59], v[112:115], v[100:103], 0
	v_mfma_f32_16x16x32_bf16 v[60:63], v[116:119], v[100:103], 0
	v_mfma_f32_16x16x32_bf16 v[64:67], v[120:123], v[100:103], 0
	v_mfma_f32_16x16x32_bf16 v[68:71], v[124:127], v[100:103], 0
	v_mfma_f32_16x16x32_bf16 v[72:75], v[128:131], v[100:103], 0
	v_mfma_f32_16x16x32_bf16 v[76:79], v[132:135], v[100:103], 0
	s_waitcnt lgkmcnt(0)
	ds_read_b64_tr_b16 v[96:97], v88 offset:16384
	ds_read_b64_tr_b16 v[98:99], v89 offset:16384
	ds_read_b64_tr_b16 v[100:101], v90 offset:16384
	ds_read_b64_tr_b16 v[102:103], v91 offset:16384
	ds_read_b64_tr_b16 v[104:105], v84 offset:16384
	ds_read_b64_tr_b16 v[106:107], v85 offset:16384
	ds_read_b64_tr_b16 v[108:109], v86 offset:16384
	ds_read_b64_tr_b16 v[110:111], v87 offset:16384
	ds_read_b64_tr_b16 v[112:113], v84 offset:16896
	ds_read_b64_tr_b16 v[114:115], v85 offset:16896
	v_mfma_f32_16x16x32_bf16 v[16:19], v[144:147], v[136:139], v[16:19]
	v_mfma_f32_16x16x32_bf16 v[20:23], v[148:151], v[136:139], v[20:23]
	v_mfma_f32_16x16x32_bf16 v[24:27], v[152:155], v[136:139], v[24:27]
	v_mfma_f32_16x16x32_bf16 v[28:31], v[156:159], v[136:139], v[28:31]
	v_mfma_f32_16x16x32_bf16 v[32:35], v[160:163], v[136:139], v[32:35]
	v_mfma_f32_16x16x32_bf16 v[36:39], v[164:167], v[136:139], v[36:39]
	v_mfma_f32_16x16x32_bf16 v[40:43], v[168:171], v[136:139], v[40:43]
	v_mfma_f32_16x16x32_bf16 v[44:47], v[172:175], v[136:139], v[44:47]
	s_waitcnt lgkmcnt(5)
	ds_read_b64_tr_b16 v[116:117], v86 offset:16896
	ds_read_b64_tr_b16 v[118:119], v87 offset:16896
	ds_read_b64_tr_b16 v[120:121], v84 offset:17408
	ds_read_b64_tr_b16 v[122:123], v85 offset:17408
	ds_read_b64_tr_b16 v[124:125], v86 offset:17408
	ds_read_b64_tr_b16 v[126:127], v87 offset:17408
	ds_read_b64_tr_b16 v[128:129], v84 offset:17920
	ds_read_b64_tr_b16 v[130:131], v85 offset:17920
	ds_read_b64_tr_b16 v[132:133], v86 offset:17920
	ds_read_b64_tr_b16 v[134:135], v87 offset:17920
	v_mfma_f32_16x16x32_bf16 v[48:51], v[144:147], v[140:143], v[48:51]
	v_mfma_f32_16x16x32_bf16 v[52:55], v[148:151], v[140:143], v[52:55]
	v_mfma_f32_16x16x32_bf16 v[56:59], v[152:155], v[140:143], v[56:59]
	v_mfma_f32_16x16x32_bf16 v[60:63], v[156:159], v[140:143], v[60:63]
	v_mfma_f32_16x16x32_bf16 v[64:67], v[160:163], v[140:143], v[64:67]
	v_mfma_f32_16x16x32_bf16 v[68:71], v[164:167], v[140:143], v[68:71]
	v_mfma_f32_16x16x32_bf16 v[72:75], v[168:171], v[140:143], v[72:75]
	v_mfma_f32_16x16x32_bf16 v[76:79], v[172:175], v[140:143], v[76:79]
	s_waitcnt lgkmcnt(0)
	ds_read_b64_tr_b16 v[136:137], v88 offset:24576
	ds_read_b64_tr_b16 v[138:139], v89 offset:24576
	ds_read_b64_tr_b16 v[140:141], v90 offset:24576
	ds_read_b64_tr_b16 v[142:143], v91 offset:24576
	ds_read_b64_tr_b16 v[144:145], v84 offset:24576
	ds_read_b64_tr_b16 v[146:147], v85 offset:24576
	ds_read_b64_tr_b16 v[148:149], v86 offset:24576
	ds_read_b64_tr_b16 v[150:151], v87 offset:24576
	ds_read_b64_tr_b16 v[152:153], v84 offset:25088
	ds_read_b64_tr_b16 v[154:155], v85 offset:25088
	v_mfma_f32_16x16x32_bf16 v[16:19], v[104:107], v[96:99], v[16:19]
	v_mfma_f32_16x16x32_bf16 v[20:23], v[108:111], v[96:99], v[20:23]
	v_mfma_f32_16x16x32_bf16 v[24:27], v[112:115], v[96:99], v[24:27]
	v_mfma_f32_16x16x32_bf16 v[28:31], v[116:119], v[96:99], v[28:31]
	v_mfma_f32_16x16x32_bf16 v[32:35], v[120:123], v[96:99], v[32:35]
	v_mfma_f32_16x16x32_bf16 v[36:39], v[124:127], v[96:99], v[36:39]
	v_mfma_f32_16x16x32_bf16 v[40:43], v[128:131], v[96:99], v[40:43]
	v_mfma_f32_16x16x32_bf16 v[44:47], v[132:135], v[96:99], v[44:47]
	s_waitcnt lgkmcnt(5)
	ds_read_b64_tr_b16 v[156:157], v86 offset:25088
	ds_read_b64_tr_b16 v[158:159], v87 offset:25088
	ds_read_b64_tr_b16 v[160:161], v84 offset:25600
	ds_read_b64_tr_b16 v[162:163], v85 offset:25600
	ds_read_b64_tr_b16 v[164:165], v86 offset:25600
	ds_read_b64_tr_b16 v[166:167], v87 offset:25600
	ds_read_b64_tr_b16 v[168:169], v84 offset:26112
	ds_read_b64_tr_b16 v[170:171], v85 offset:26112
	ds_read_b64_tr_b16 v[172:173], v86 offset:26112
	ds_read_b64_tr_b16 v[174:175], v87 offset:26112
	v_mfma_f32_16x16x32_bf16 v[48:51], v[104:107], v[100:103], v[48:51]
	v_mfma_f32_16x16x32_bf16 v[52:55], v[108:111], v[100:103], v[52:55]
	v_mfma_f32_16x16x32_bf16 v[56:59], v[112:115], v[100:103], v[56:59]
	v_mfma_f32_16x16x32_bf16 v[60:63], v[116:119], v[100:103], v[60:63]
	v_mfma_f32_16x16x32_bf16 v[64:67], v[120:123], v[100:103], v[64:67]
	v_mfma_f32_16x16x32_bf16 v[68:71], v[124:127], v[100:103], v[68:71]
	v_mfma_f32_16x16x32_bf16 v[72:75], v[128:131], v[100:103], v[72:75]
	v_mfma_f32_16x16x32_bf16 v[76:79], v[132:135], v[100:103], v[76:79]
	s_waitcnt lgkmcnt(0)
	v_mfma_f32_16x16x32_bf16 v[16:19], v[144:147], v[136:139], v[16:19]
	v_mfma_f32_16x16x32_bf16 v[20:23], v[148:151], v[136:139], v[20:23]
	v_mfma_f32_16x16x32_bf16 v[24:27], v[152:155], v[136:139], v[24:27]
	v_mfma_f32_16x16x32_bf16 v[28:31], v[156:159], v[136:139], v[28:31]
	v_mfma_f32_16x16x32_bf16 v[32:35], v[160:163], v[136:139], v[32:35]
	v_mfma_f32_16x16x32_bf16 v[36:39], v[164:167], v[136:139], v[36:39]
	v_mfma_f32_16x16x32_bf16 v[40:43], v[168:171], v[136:139], v[40:43]
	v_mfma_f32_16x16x32_bf16 v[44:47], v[172:175], v[136:139], v[44:47]
	v_mfma_f32_16x16x32_bf16 v[48:51], v[144:147], v[140:143], v[48:51]
	v_mfma_f32_16x16x32_bf16 v[52:55], v[148:151], v[140:143], v[52:55]
	v_mfma_f32_16x16x32_bf16 v[56:59], v[152:155], v[140:143], v[56:59]
	v_mfma_f32_16x16x32_bf16 v[60:63], v[156:159], v[140:143], v[60:63]
	v_mfma_f32_16x16x32_bf16 v[64:67], v[160:163], v[140:143], v[64:67]
	v_mfma_f32_16x16x32_bf16 v[68:71], v[164:167], v[140:143], v[68:71]
	v_mfma_f32_16x16x32_bf16 v[72:75], v[168:171], v[140:143], v[72:75]
	v_mfma_f32_16x16x32_bf16 v[76:79], v[172:175], v[140:143], v[76:79]
	v_readlane_b32 s4, v254, 9
	v_readlane_b32 s5, v254, 10
	v_lshrrev_b32_e32 v0, 6, v201
	v_lshlrev_b32_e32 v0, 5, v0
	v_and_b32_e32 v2, 15, v201
	v_add_u32_e32 v0, v0, v2
	v_lshlrev_b32_e32 v0, 9, v0
	v_bfe_u32 v2, v201, 4, 2
	v_lshl_add_u32 v0, v2, 4, v0
	s_lshl_b32 s8, s6, 15
	s_mov_b32 s9, 0
	s_mov_b32 s98, 0x2000
	s_mov_b32 s99, 0
	v_lshl_add_u64 v[10:11], s[4:5], 0, v[0:1]
	v_lshl_add_u64 v[10:11], v[10:11], 0, s[8:9]
	v_lshl_add_u64 v[12:13], v[10:11], 0, s[98:99]
	s_nop 7
	s_nop 7
	s_nop 7
	s_nop 7
	global_store_dwordx4 v[10:11], v[16:19], off
	global_store_dwordx4 v[10:11], v[20:23], off offset:64
	global_store_dwordx4 v[10:11], v[24:27], off offset:128
	global_store_dwordx4 v[10:11], v[28:31], off offset:192
	global_store_dwordx4 v[10:11], v[32:35], off offset:256
	global_store_dwordx4 v[10:11], v[36:39], off offset:320
	global_store_dwordx4 v[10:11], v[40:43], off offset:384
	global_store_dwordx4 v[10:11], v[44:47], off offset:448
	global_store_dwordx4 v[12:13], v[48:51], off
	global_store_dwordx4 v[12:13], v[52:55], off offset:64
	global_store_dwordx4 v[12:13], v[56:59], off offset:128
	global_store_dwordx4 v[12:13], v[60:63], off offset:192
	global_store_dwordx4 v[12:13], v[64:67], off offset:256
	global_store_dwordx4 v[12:13], v[68:71], off offset:320
	global_store_dwordx4 v[12:13], v[72:75], off offset:384
	global_store_dwordx4 v[12:13], v[76:79], off offset:448
	s_mov_b64 s[4:5], 0

.LBB0_469:
	s_add_i32 s31, s24, 0xfffffd60
	s_and_b32 s2, s31, 7
	s_lshl_b32 s2, s2, 5
	s_lshr_b32 s31, s31, 3
	s_or_b32 s31, s31, s2
	v_mov_b32_e32 v51, v201
	s_cmpk_gt_u32 s31, 0xbff
	s_cbranch_scc1 .LBB0_508
	s_and_b32 s2, s31, 0xffff
	s_mul_i32 s2, s2, 0xaaab
	s_lshr_b32 s4, s2, 23
	s_mulk_i32 s4, 0xc0
	s_sub_i32 s4, s31, s4
	s_and_b32 s6, s4, 63
	s_lshr_b32 s4, s4, 5
	s_and_b32 s5, s4, 6
	s_lshr_b32 s4, 64, s5
	s_add_i32 s4, s4, -1
	s_and_b32 s4, s4, s6
	s_lshl_b32 s8, s4, 7
	s_xor_b32 s7, s5, 6
	s_add_i32 s10, s8, 0xffffff80
	s_lshr_b32 s4, s2, 12
	v_lshlrev_b32_e32 v0, 3, v51
	v_ashrrev_i32_e32 v90, 3, v51
	s_lshr_b32 s7, s6, s7
	s_and_b32 s4, s4, 0xe000
	s_lshr_b32 s2, s2, 17
	v_and_b32_e32 v36, 56, v0
	v_add_u32_e32 v0, s10, v90
	v_mov_b32 v4, 0
	s_or_b32 s4, s7, s4
	v_mov_b32_e32 v5, v4
	s_and_b32 s9, s2, 0xc0
	v_cmp_lt_i32_e32 vcc, -1, v0
	v_lshlrev_b32_e32 v78, 1, v36
	v_mov_b64_e32 v[2:3], v[4:5]
	v_mov_b64_e32 v[18:19], v[4:5]
	v_mov_b64_e32 v[20:21], v[4:5]
	s_and_saveexec_b64 s[6:7], vcc
	s_cbranch_execz .LBB0_472
	v_readlane_b32 s12, v254, 1
	v_lshlrev_b32_e32 v0, s5, v0
	v_readlane_b32 s13, v254, 2
	v_add_u32_e32 v0, s4, v0
	s_movk_i32 s2, 0x1400
	v_mov_b64_e32 v[2:3], s[12:13]
	v_mad_i64_i32 v[2:3], s[12:13], v0, s2, v[2:3]
	s_lshl_b32 s2, s9, 1
	v_lshl_add_u64 v[2:3], v[2:3], 0, s[2:3]
	v_mov_b32_e32 v79, v1
	v_lshl_add_u64 v[2:3], v[2:3], 0, v[78:79]
	global_load_dwordx4 v[18:21], v[2:3], off offset:1536
	s_nop 0
	global_load_dwordx4 v[2:5], v[2:3], off offset:1024

.LBB0_478:
	s_or_b64 exec, exec, s[6:7]
	v_and_b32_e32 v94, 0xff, v51
	s_lshl_b32 s2, s9, 1
	v_ashrrev_i32_e32 v53, 5, v51
	v_and_b32_e32 v80, -8, v53
	v_ashrrev_i32_e32 v55, 5, v52
	v_and_b32_e32 v82, -8, v55
	v_ashrrev_i32_e32 v56, 5, v0
	v_and_b32_e32 v84, -8, v56
	v_ashrrev_i32_e32 v57, 5, v54
	v_and_b32_e32 v86, -8, v57
	v_ashrrev_i32_e32 v87, 31, v86
	v_and_b32_e32 v35, 15, v51
	v_ashrrev_i32_e32 v50, 2, v51
	v_or_b32_e32 v0, s8, v35
	v_and_b32_e32 v34, -16, v50
	v_add_u32_e32 v38, v0, v34
	v_ashrrev_i32_e32 v39, 31, v38
	v_lshlrev_b64 v[38:39], s5, v[38:39]
	s_mov_b32 s5, s3
	v_lshl_add_u64 v[38:39], v[38:39], 0, s[4:5]
	v_readlane_b32 s4, v254, 1
	v_readlane_b32 s5, v254, 2
	s_movk_i32 s6, 0x1400
	v_bfe_u32 v58, v51, 4, 2
	v_mov_b64_e32 v[40:41], s[4:5]
	v_mad_u64_u32 v[40:41], s[4:5], v38, s6, v[40:41]
	v_ashrrev_i32_e32 v37, 6, v51
	v_cmp_eq_u32_e64 s[4:5], 0, v58
	v_mad_i32_i24 v41, v39, s6, v41
	v_lshrrev_b32_e32 v0, 1, v51
	v_bfi_b32 v95, -16, v50, v51
	v_lshlrev_b32_e32 v59, 4, v37
	v_writelane_b32 v254, s4, 24
	v_lshrrev_b32_e32 v51, 6, v51
	v_lshrrev_b32_e32 v52, 6, v52
	v_lshl_add_u64 v[38:39], v[40:41], 0, s[2:3]
	v_or_b32_e32 v96, v59, v35
	v_writelane_b32 v254, s5, 25
	s_movk_i32 s2, 0x90
	v_and_b32_e32 v62, 12, v51
	s_mov_b32 s4, 0xfffffe0
	v_and_b32_e32 v52, 12, v52
	v_and_b32_e32 v34, 24, v0
	v_and_or_b32 v51, v53, s4, v62
	v_and_or_b32 v52, v55, s4, v52
	v_and_or_b32 v53, v56, s4, v62
	v_lshrrev_b32_e32 v54, 6, v54
	v_mul_lo_u32 v55, v96, s2
	v_lshlrev_b32_e32 v56, 4, v58
	v_lshlrev_b32_e32 v0, 1, v34
	v_and_b32_e32 v54, 12, v54
	v_add3_u32 v97, 0, v55, v56
	v_add_u32_e32 v55, 1, v37
	v_lshl_add_u64 v[38:39], v[38:39], 0, v[0:1]
	v_and_or_b32 v54, v57, s4, v54
	v_lshlrev_b32_e32 v57, 4, v55
	global_load_dwordx4 v[42:45], v[38:39], off offset:576
	global_load_dwordx4 v[46:49], v[38:39], off offset:512
	v_lshl_add_u32 v38, v36, 1, 0
	v_lshlrev_b32_e32 v36, 3, v58
	v_lshlrev_b32_e32 v60, 2, v58
	v_or_b32_e32 v58, v57, v35
	v_mul_lo_u32 v58, v58, s2
	v_add3_u32 v98, 0, v58, v56
	v_add_u32_e32 v58, 2, v37
	v_lshlrev_b32_e32 v62, 4, v58
	v_or_b32_e32 v63, v62, v35
	v_mul_lo_u32 v63, v63, s2
	v_add3_u32 v99, 0, v63, v56
	v_add_u32_e32 v63, 3, v37
	v_lshlrev_b32_e32 v64, 4, v63
	v_or_b32_e32 v65, v64, v35
	v_mul_lo_u32 v65, v65, s2
	v_add3_u32 v100, 0, v65, v56
	v_add_u32_e32 v65, 4, v37
	v_lshlrev_b32_e32 v66, 4, v65
	v_or_b32_e32 v67, v66, v35
	v_mul_lo_u32 v67, v67, s2
	v_add3_u32 v101, 0, v67, v56
	v_add_u32_e32 v67, 5, v37
	v_lshlrev_b32_e32 v68, 4, v67
	v_or_b32_e32 v69, v68, v35
	v_mul_lo_u32 v69, v69, s2
	v_add3_u32 v102, 0, v69, v56
	v_add_u32_e32 v69, 6, v37
	v_lshlrev_b32_e32 v70, 4, v69
	v_or_b32_e32 v71, v70, v35
	v_mul_lo_u32 v71, v71, s2
	v_add3_u32 v103, 0, v71, v56
	v_add_u32_e32 v71, 7, v37
	v_lshlrev_b32_e32 v72, 4, v71
	v_or_b32_e32 v73, v72, v35
	v_mul_lo_u32 v73, v73, s2
	v_add3_u32 v104, 0, v73, v56
	v_add_u32_e32 v73, 8, v37
	v_lshlrev_b32_e32 v74, 4, v73
	v_or_b32_e32 v75, v74, v35
	v_mul_lo_u32 v75, v75, s2
	v_add_u32_e32 v61, 0x80, v96
	v_add3_u32 v105, 0, v75, v56
	v_or_b32_e32 v56, v60, v59
	v_mul_lo_u32 v39, v90, s2
	v_mul_lo_u32 v40, v91, s2
	v_mul_lo_u32 v41, v92, s2
	v_mul_lo_u32 v50, v93, s2
	v_sub_u32_e32 v59, v61, v56
	s_movk_i32 s18, 0x81
	s_movk_i32 s2, 0x100
	v_cmp_gt_u32_e32 vcc, s18, v59
	v_cmp_gt_i32_e64 s[4:5], s2, v56
	s_and_b64 s[4:5], s[4:5], vcc
	s_movk_i32 s28, 0x7f
	v_writelane_b32 v254, s4, 9
	v_or_b32_e32 v59, 1, v56
	v_sub_u32_e32 v75, v61, v59
	v_writelane_b32 v254, s5, 10
	v_cmp_lt_i32_e64 s[4:5], s28, v56
	v_cmp_gt_u32_e32 vcc, s18, v75
	s_movk_i32 s16, 0x7e
	v_writelane_b32 v253, s4, 59
	s_movk_i32 s29, 0x230
	v_mad_u32_u24 v35, v35, s29, 0
	v_writelane_b32 v253, s5, 60
	v_cmp_gt_i32_e64 s[4:5], s2, v59
	s_and_b64 s[4:5], s[4:5], vcc
	v_or_b32_e32 v59, 2, v56
	v_writelane_b32 v254, s4, 20
	v_sub_u32_e32 v75, v61, v59
	v_cmp_gt_u32_e32 vcc, s18, v75
	v_writelane_b32 v254, s5, 21
	v_cmp_lt_i32_e64 s[4:5], s16, v56
	v_or_b32_e32 v56, 3, v56
	v_lshlrev_b32_e32 v37, 5, v37
	v_writelane_b32 v254, s4, 22
	v_lshlrev_b32_e32 v55, 5, v55
	v_add3_u32 v107, v35, v37, v36
	v_writelane_b32 v254, s5, 23
	v_cmp_gt_i32_e64 s[4:5], s2, v59
	s_and_b64 s[4:5], s[4:5], vcc
	v_add3_u32 v106, v35, v55, v36
	v_writelane_b32 v254, s4, 26
	v_lshl_add_u32 v0, v94, 1, 0
	v_mul_lo_u32 v51, v51, s29
	v_writelane_b32 v254, s5, 27
	v_cmp_lt_i32_e64 s[4:5], s28, v59
	v_sub_u32_e32 v59, v61, v56
	v_cmp_gt_u32_e32 vcc, s18, v59
	v_writelane_b32 v254, s4, 28
	v_mul_lo_u32 v52, v52, s29
	v_mul_lo_u32 v53, v53, s29
	v_writelane_b32 v254, s5, 29
	v_cmp_gt_i32_e64 s[4:5], s2, v56
	s_and_b64 s[4:5], s[4:5], vcc
	v_mul_lo_u32 v54, v54, s29
	v_writelane_b32 v254, s4, 30
	v_add_u32_e32 v124, v38, v39
	v_add_u32_e32 v125, v38, v40
	v_writelane_b32 v254, s5, 31
	v_cmp_lt_i32_e64 s[4:5], s28, v56
	v_or_b32_e32 v56, v57, v60
	v_sub_u32_e32 v57, v61, v56
	v_writelane_b32 v254, s4, 32
	v_cmp_gt_u32_e32 vcc, s18, v57
	v_or_b32_e32 v57, 1, v56
	v_writelane_b32 v254, s5, 33
	v_cmp_gt_i32_e64 s[4:5], s2, v56
	s_and_b64 s[4:5], s[4:5], vcc
	v_sub_u32_e32 v59, v61, v57
	v_writelane_b32 v254, s4, 34
	v_cmp_gt_u32_e32 vcc, s18, v59
	v_add_u32_e32 v126, v38, v41
	v_writelane_b32 v254, s5, 35
	v_cmp_lt_i32_e64 s[4:5], s28, v56
	v_add_u32_e32 v127, v38, v50
	v_add_u32_e32 v128, v0, v51
	v_writelane_b32 v254, s4, 36
	v_add_u32_e32 v129, v0, v52
	v_add_u32_e32 v130, v0, v53
	v_writelane_b32 v254, s5, 37
	v_cmp_gt_i32_e64 s[4:5], s2, v57
	s_and_b64 s[4:5], s[4:5], vcc
	v_or_b32_e32 v57, 2, v56
	v_writelane_b32 v254, s4, 38
	v_sub_u32_e32 v59, v61, v57
	v_cmp_gt_u32_e32 vcc, s18, v59
	v_writelane_b32 v254, s5, 39
	v_cmp_lt_i32_e64 s[4:5], s16, v56
	v_or_b32_e32 v56, 3, v56
	v_add_u32_e32 v131, v0, v54
	v_writelane_b32 v254, s4, 40
	v_lshlrev_b32_e32 v0, 1, v34
	v_lshlrev_b32_e32 v88, 1, v36
	v_writelane_b32 v254, s5, 41
	v_cmp_gt_i32_e64 s[4:5], s2, v57
	s_and_b64 s[4:5], s[4:5], vcc
	s_waitcnt vmcnt(1)
	v_mov_b64_e32 v[38:39], v[42:43]
	v_writelane_b32 v254, s4, 42
	v_ashrrev_i32_e32 v81, 31, v80
	v_ashrrev_i32_e32 v83, 31, v82
	v_writelane_b32 v254, s5, 43
	v_cmp_lt_i32_e64 s[4:5], s28, v57
	v_sub_u32_e32 v57, v61, v56
	v_cmp_gt_u32_e32 vcc, s18, v57
	v_writelane_b32 v254, s4, 44
	v_ashrrev_i32_e32 v85, 31, v84
	v_mov_b64_e32 v[40:41], v[44:45]
	v_writelane_b32 v254, s5, 45
	v_cmp_gt_i32_e64 s[4:5], s2, v56
	s_and_b64 s[4:5], s[4:5], vcc
	s_nop 0
	v_writelane_b32 v254, s4, 46
	s_nop 1
	v_writelane_b32 v254, s5, 47
	v_cmp_lt_i32_e64 s[4:5], s28, v56
	v_or_b32_e32 v56, v62, v60
	v_sub_u32_e32 v57, v61, v56
	v_writelane_b32 v254, s4, 48
	v_cmp_gt_u32_e32 vcc, s18, v57
	v_or_b32_e32 v57, 1, v56
	v_writelane_b32 v254, s5, 49
	v_cmp_gt_i32_e64 s[4:5], s2, v56
	s_and_b64 s[4:5], s[4:5], vcc
	v_sub_u32_e32 v59, v61, v57
	v_writelane_b32 v254, s4, 50
	v_cmp_gt_u32_e32 vcc, s18, v59
	s_nop 0
	v_writelane_b32 v254, s5, 51
	v_cmp_lt_i32_e64 s[4:5], s28, v56
	s_nop 1
	v_writelane_b32 v254, s4, 52
	s_nop 1
	v_writelane_b32 v254, s5, 53
	v_cmp_gt_i32_e64 s[4:5], s2, v57
	s_and_b64 s[4:5], s[4:5], vcc
	v_or_b32_e32 v57, 2, v56
	v_writelane_b32 v254, s4, 54
	v_sub_u32_e32 v59, v61, v57
	v_cmp_gt_u32_e32 vcc, s18, v59
	v_writelane_b32 v254, s5, 55
	v_cmp_lt_i32_e64 s[4:5], s16, v56
	v_or_b32_e32 v56, 3, v56
	s_nop 0
	v_writelane_b32 v254, s4, 56
	s_nop 1
	v_writelane_b32 v254, s5, 57
	v_cmp_gt_i32_e64 s[4:5], s2, v57
	s_and_b64 s[4:5], s[4:5], vcc
	s_nop 0
	v_writelane_b32 v254, s4, 58
	s_nop 1
	v_writelane_b32 v254, s5, 59
	v_cmp_lt_i32_e64 s[4:5], s28, v57
	v_sub_u32_e32 v57, v61, v56
	v_cmp_gt_u32_e32 vcc, s18, v57
	v_writelane_b32 v254, s4, 60
	s_nop 1
	v_writelane_b32 v254, s5, 61
	v_cmp_gt_i32_e64 s[4:5], s2, v56
	s_and_b64 s[4:5], s[4:5], vcc
	s_nop 0
	v_writelane_b32 v254, s4, 62
	s_nop 1
	v_writelane_b32 v254, s5, 63
	v_cmp_lt_i32_e64 s[4:5], s28, v56
	v_or_b32_e32 v56, v64, v60
	v_sub_u32_e32 v57, v61, v56
	v_writelane_b32 v255, s4, 0
	v_cmp_gt_u32_e32 vcc, s18, v57
	v_or_b32_e32 v57, 1, v56
	v_writelane_b32 v255, s5, 1
	v_cmp_gt_i32_e64 s[4:5], s2, v56
	s_and_b64 s[4:5], s[4:5], vcc
	v_sub_u32_e32 v59, v61, v57
	v_writelane_b32 v255, s4, 2
	v_cmp_gt_u32_e32 vcc, s18, v59
	s_nop 0
	v_writelane_b32 v255, s5, 3
	v_cmp_lt_i32_e64 s[4:5], s28, v56
	s_nop 1
	v_writelane_b32 v255, s4, 4
	s_nop 1
	v_writelane_b32 v255, s5, 5
	v_cmp_gt_i32_e64 s[4:5], s2, v57
	s_and_b64 s[4:5], s[4:5], vcc
	v_or_b32_e32 v57, 2, v56
	v_writelane_b32 v255, s4, 6
	v_sub_u32_e32 v59, v61, v57
	v_cmp_gt_u32_e32 vcc, s18, v59
	v_writelane_b32 v255, s5, 7
	v_cmp_lt_i32_e64 s[4:5], s16, v56
	v_or_b32_e32 v56, 3, v56
	s_nop 0
	v_writelane_b32 v255, s4, 8
	s_nop 1
	v_writelane_b32 v255, s5, 9
	v_cmp_gt_i32_e64 s[4:5], s2, v57
	s_and_b64 s[4:5], s[4:5], vcc
	s_nop 0
	v_writelane_b32 v255, s4, 10
	s_nop 1
	v_writelane_b32 v255, s5, 11
	v_cmp_lt_i32_e64 s[4:5], s28, v57
	v_sub_u32_e32 v57, v61, v56
	v_cmp_gt_u32_e32 vcc, s18, v57
	v_writelane_b32 v255, s4, 12
	s_nop 1
	v_writelane_b32 v255, s5, 13
	v_cmp_gt_i32_e64 s[4:5], s2, v56
	s_and_b64 s[4:5], s[4:5], vcc
	s_nop 0
	v_writelane_b32 v255, s4, 14
	s_nop 1
	v_writelane_b32 v255, s5, 15
	v_cmp_lt_i32_e64 s[4:5], s28, v56
	v_or_b32_e32 v56, v66, v60
	v_sub_u32_e32 v57, v61, v56
	v_writelane_b32 v255, s4, 16
	v_cmp_gt_u32_e32 vcc, s18, v57
	v_or_b32_e32 v57, 1, v56
	v_writelane_b32 v255, s5, 17
	v_cmp_gt_i32_e64 s[4:5], s2, v56
	s_and_b64 s[40:41], s[4:5], vcc
	v_sub_u32_e32 v59, v61, v57
	v_cmp_gt_i32_e64 s[4:5], s2, v57
	v_or_b32_e32 v57, 2, v56
	v_cmp_gt_u32_e32 vcc, s18, v59
	v_sub_u32_e32 v59, v61, v57
	v_cmp_lt_i32_e64 s[74:75], s28, v56
	s_and_b64 s[52:53], s[4:5], vcc
	v_cmp_lt_i32_e64 s[76:77], s16, v56
	v_cmp_gt_u32_e32 vcc, s18, v59
	v_cmp_gt_i32_e64 s[4:5], s2, v57
	v_or_b32_e32 v56, 3, v56
	s_and_b64 s[20:21], s[4:5], vcc
	v_cmp_lt_i32_e64 s[78:79], s28, v57
	v_sub_u32_e32 v57, v61, v56
	v_cmp_gt_i32_e64 s[4:5], s2, v56
	v_cmp_lt_i32_e64 s[80:81], s28, v56
	v_or_b32_e32 v56, v68, v60
	v_cmp_gt_u32_e32 vcc, s18, v57
	v_sub_u32_e32 v57, v61, v56
	s_and_b64 s[54:55], s[4:5], vcc
	v_cmp_gt_u32_e32 vcc, s18, v57
	v_cmp_gt_i32_e64 s[4:5], s2, v56
	v_or_b32_e32 v57, 1, v56
	s_and_b64 s[42:43], s[4:5], vcc
	v_sub_u32_e32 v59, v61, v57
	v_cmp_gt_i32_e64 s[4:5], s2, v57
	v_or_b32_e32 v57, 2, v56
	v_cmp_gt_u32_e32 vcc, s18, v59
	v_sub_u32_e32 v59, v61, v57
	v_cmp_lt_i32_e64 s[82:83], s28, v56
	s_and_b64 s[56:57], s[4:5], vcc
	v_cmp_lt_i32_e64 s[84:85], s16, v56
	v_cmp_gt_u32_e32 vcc, s18, v59
	v_cmp_gt_i32_e64 s[4:5], s2, v57
	v_or_b32_e32 v56, 3, v56
	s_and_b64 s[22:23], s[4:5], vcc
	v_cmp_lt_i32_e64 s[86:87], s28, v57
	v_sub_u32_e32 v57, v61, v56
	v_cmp_gt_i32_e64 s[4:5], s2, v56
	v_cmp_lt_i32_e64 s[88:89], s28, v56
	v_or_b32_e32 v56, v70, v60
	v_cmp_gt_u32_e32 vcc, s18, v57
	v_sub_u32_e32 v57, v61, v56
	s_and_b64 s[58:59], s[4:5], vcc
	v_cmp_gt_u32_e32 vcc, s18, v57
	v_cmp_gt_i32_e64 s[4:5], s2, v56
	v_or_b32_e32 v57, 1, v56
	s_and_b64 s[44:45], s[4:5], vcc
	v_sub_u32_e32 v59, v61, v57
	v_cmp_gt_i32_e64 s[4:5], s2, v57
	v_or_b32_e32 v57, 2, v56
	v_cmp_gt_u32_e32 vcc, s18, v59
	v_sub_u32_e32 v59, v61, v57
	v_cmp_lt_i32_e64 s[90:91], s28, v56
	s_and_b64 s[60:61], s[4:5], vcc
	v_cmp_lt_i32_e64 s[92:93], s16, v56
	v_cmp_gt_u32_e32 vcc, s18, v59
	v_cmp_gt_i32_e64 s[4:5], s2, v57
	v_or_b32_e32 v56, 3, v56
	s_and_b64 s[24:25], s[4:5], vcc
	v_cmp_lt_i32_e64 s[94:95], s28, v57
	v_sub_u32_e32 v57, v61, v56
	v_cmp_gt_i32_e64 s[4:5], s2, v56
	v_cmp_lt_i32_e64 s[96:97], s28, v56
	v_or_b32_e32 v56, v72, v60
	v_cmp_gt_u32_e32 vcc, s18, v57
	v_sub_u32_e32 v57, v61, v56
	s_and_b64 s[62:63], s[4:5], vcc
	v_cmp_gt_u32_e32 vcc, s18, v57
	v_or_b32_e32 v57, 1, v56
	v_cmp_gt_i32_e64 s[4:5], s2, v56
	v_sub_u32_e32 v59, v61, v57
	v_cmp_gt_i32_e64 s[6:7], s2, v57
	v_or_b32_e32 v57, 2, v56
	s_and_b64 s[46:47], s[4:5], vcc
	v_cmp_gt_u32_e32 vcc, s18, v59
	v_sub_u32_e32 v59, v61, v57
	v_cmp_lt_i32_e64 s[4:5], s28, v56
	s_and_b64 s[64:65], s[6:7], vcc
	v_cmp_lt_i32_e64 s[6:7], s16, v56
	v_cmp_gt_u32_e32 vcc, s18, v59
	v_cmp_gt_i32_e64 s[8:9], s2, v57
	v_or_b32_e32 v56, 3, v56
	s_and_b64 s[26:27], s[8:9], vcc
	v_cmp_lt_i32_e64 s[8:9], s28, v57
	v_sub_u32_e32 v57, v61, v56
	v_cmp_gt_u32_e32 vcc, s18, v57
	v_cmp_gt_i32_e64 s[10:11], s2, v56
	s_and_b64 s[66:67], s[10:11], vcc
	v_cmp_lt_i32_e64 s[10:11], s28, v56
	v_or_b32_e32 v56, v74, v60
	v_sub_u32_e32 v57, v61, v56
	v_cmp_gt_u32_e32 vcc, s18, v57
	v_or_b32_e32 v57, 1, v56
	v_cmp_gt_i32_e64 s[12:13], s2, v56
	v_sub_u32_e32 v59, v61, v57
	v_cmp_gt_i32_e64 s[14:15], s2, v57
	v_or_b32_e32 v57, 2, v56
	s_and_b64 s[48:49], s[12:13], vcc
	v_cmp_gt_u32_e32 vcc, s18, v59
	v_sub_u32_e32 v59, v61, v57
	v_cmp_lt_i32_e64 s[12:13], s28, v56
	s_and_b64 s[68:69], s[14:15], vcc
	v_cmp_lt_i32_e64 s[14:15], s16, v56
	v_cmp_gt_u32_e32 vcc, s18, v59
	v_cmp_gt_i32_e64 s[16:17], s2, v57
	v_or_b32_e32 v56, 3, v56
	s_and_b64 s[38:39], s[16:17], vcc
	v_cmp_lt_i32_e64 s[16:17], s28, v57
	v_sub_u32_e32 v57, v61, v56
	v_cmp_gt_u32_e32 vcc, s18, v57
	v_cmp_gt_i32_e64 s[18:19], s2, v56
	s_and_b64 s[70:71], s[18:19], vcc
	v_cmp_lt_i32_e64 s[18:19], s28, v56
	v_add_u32_e32 v56, 0x9900, v35
	v_add3_u32 v108, v56, v37, v36
	v_lshlrev_b32_e32 v37, 5, v58
	v_add3_u32 v109, v56, v55, v36
	v_lshlrev_b32_e32 v55, 5, v63
	v_add3_u32 v111, v35, v37, v36
	v_add3_u32 v112, v56, v37, v36
	v_lshlrev_b32_e32 v37, 5, v65
	v_add3_u32 v110, v35, v55, v36
	v_add3_u32 v113, v56, v55, v36
	v_lshlrev_b32_e32 v55, 5, v67
	v_add3_u32 v115, v35, v37, v36
	v_add3_u32 v116, v56, v37, v36
	v_lshlrev_b32_e32 v37, 5, v69
	v_add3_u32 v114, v35, v55, v36
	v_add3_u32 v117, v56, v55, v36
	v_lshlrev_b32_e32 v55, 5, v71
	v_add3_u32 v119, v35, v37, v36
	v_add3_u32 v120, v56, v37, v36
	v_lshlrev_b32_e32 v37, 5, v73
	v_add3_u32 v118, v35, v55, v36
	v_add3_u32 v121, v56, v55, v36
	v_add3_u32 v122, v35, v37, v36
	v_add3_u32 v123, v56, v37, v36
	v_and_b32_e32 v131, 7, v201
	v_bfe_u32 v106, v201, 3, 3
	v_lshrrev_b32_e32 v107, 6, v201
	v_lshrrev_b32_e32 v108, 2, v131
	v_and_b32_e32 v109, 3, v131
	v_lshlrev_b32_e32 v110, 5, v106
	v_lshl_add_u32 v110, v109, 3, v110
	v_lshl_add_u32 v110, v108, 6, v110
	v_and_b32_e32 v110, 0xff, v110
	v_lshl_add_u32 v110, v108, 9, v110
	v_lshl_add_u32 v128, v107, 10, v110
	v_and_b32_e32 v111, 63, v201
	v_and_b32_e32 v112, 15, v111
	v_lshrrev_b32_e32 v113, 4, v111
	v_and_b32_e32 v114, 1, v113
	v_lshrrev_b32_e32 v115, 1, v113
	v_lshrrev_b32_e32 v116, 2, v112
	v_and_b32_e32 v117, 3, v112
	v_lshl_add_u32 v116, v114, 2, v116
	v_lshlrev_b32_e32 v116, 5, v116
	v_lshl_add_u32 v116, v117, 3, v116
	v_lshlrev_b32_e32 v118, 11, v107
	v_lshl_add_u32 v118, v115, 10, v118
	v_add_u32_e32 v129, v118, v116
	v_add_u32_e32 v116, 64, v116
	v_and_b32_e32 v116, 0xff, v116
	v_add_u32_e32 v130, v118, v116
	v_add_u32_e32 v130, 0x200, v130
	s_waitcnt vmcnt(0)
	v_mov_b64_e32 v[34:35], v[46:47]
	v_mov_b64_e32 v[36:37], v[48:49]
	s_branch .LBB0_488
	s_nop 0
	s_nop 0
	s_nop 0
	s_nop 0
	s_nop 0
	s_nop 0
	s_nop 0
	s_nop 0
	s_nop 0
	s_nop 0
	s_nop 0
	s_nop 0
